# W_in epilogue transposed-V stores: neighbouring token lanes exchange rounded bf16 via DPP so each lane stores one dword (2 tokens) instead of two 2-byte stores
# speedup vs baseline: 1.0151x; 1.0015x over previous
; #define LAS __attribute__((address_space(3)))
; __global__ void __launch_bounds__(512, 2) fwd_megakernel(Params p, int ph_lo, int ph_hi) {
;   extern __shared__ __attribute__((aligned(16))) char smem[];
;   cg::grid_group grid = cg::this_grid();
;   volatile LAS unsigned* st = (volatile LAS unsigned*)((LAS unsigned char*)smem + 131072);
;   if (threadIdx.x == 0) { st[0] = 0u; st[1] = 0u; st[2] = 0u; st[3] = 0u; }
;   __syncthreads();
;   XcdBarrier xb = xcd_barrier_post(reinterpret_cast<unsigned*>(p.ws + OFF_BAR), st);
; #pragma unroll 1
;   for (int ph = ph_lo; ph <= ph_hi; ++ph) {
;     int tid512 = (int)__builtin_amdgcn_workitem_id_x();
;     asm volatile("" : "+v"(tid512));
;     run_phase(tid512, p, ph);
;     if (ph < ph_hi) {
;       if (ph == 0) grid.sync();
;       else xcd_barrier(xb);
;     }
;   }
.LBB0_340:
.LBB0_341:
	v_readlane_b32 s0, v255, 19
	v_readlane_b32 s1, v255, 20
	s_branch .LBB0_797
.Ltramp_960:
	s_branch .LBB0_960
.Ltramp_10:
	s_branch .LBB0_10
.LBB0_342:
	s_or_b64 exec, exec, s[12:13]
	v_readlane_b32 s78, v255, 7
	v_readlane_b32 s80, v255, 9
	v_readlane_b32 s82, v255, 11
	v_readlane_b32 s40, v255, 13
	v_readlane_b32 s84, v255, 16
	s_mov_b64 s[0:1], 0
	v_readlane_b32 s79, v255, 8
	v_readlane_b32 s81, v255, 10
	v_readlane_b32 s83, v255, 12
	v_readlane_b32 s41, v255, 14
	v_readlane_b32 s75, v255, 15
	v_readlane_b32 s85, v255, 17

; __device__ __forceinline__ bfu f2bf(float f) {
;   unsigned u = __float_as_uint(f);
;   u += 0x7fffu + ((u >> 16) & 1u);
;   return (bfu)(u >> 16);
; }
;   __device__ __forceinline__ void operator()(const f32x4 (&acc)[2][2][4][2], const Unit& u, int wr, int wc, int fr, int fq) const {
;     ...
;           } else if (sec == 11) {
;             const int t = tbase + rl;
;             bfu* dst = vt + ((size_t)bb * 512 + (c0 - 5632)) * TPB + t;
; #pragma unroll
;             for (int j = 0; j < 4; ++j) {
;               dst[(size_t)j * TPB] = f2bf(v0[j]);
;               dst[(size_t)(16 + j) * TPB] = f2bf(v1[j]);
;             }
.LBB0_378:
	s_andn2_b64 vcc, exec, s[44:45]
	s_cbranch_vccnz .LBB0_380
	v_readlane_b32 s6, v252, 45
	v_add_u32_e32 v124, s20, v156
	v_readlane_b32 s7, v252, 46
	v_ashrrev_i32_e32 v125, 31, v124
	s_nop 0
	v_lshl_add_u64 v[126:127], s[6:7], 0, v[170:171]
	v_lshl_add_u64 v[124:125], v[124:125], 1, v[126:127]
	v_bfe_u32 v126, v132, 16, 1
	v_add3_u32 v132, v132, v126, s94
	v_bfe_u32 v126, v133, 16, 1
	v_add3_u32 v133, v133, v126, s94
	v_bfe_u32 v126, v134, 16, 1
	v_add3_u32 v134, v134, v126, s94
	v_bfe_u32 v126, v135, 16, 1
	v_add3_u32 v135, v135, v126, s94
	v_bfe_u32 v126, v136, 16, 1
	v_add3_u32 v136, v136, v126, s94
	v_bfe_u32 v126, v137, 16, 1
	v_add3_u32 v137, v137, v126, s94
	v_bfe_u32 v126, v138, 16, 1
	v_add3_u32 v138, v138, v126, s94
	v_bfe_u32 v126, v139, 16, 1
	v_add3_u32 v139, v139, v126, s94
	s_mov_b32 vcc_lo, 0xaaaaaaaa
	s_mov_b32 vcc_hi, 0xaaaaaaaa
	v_mov_b32_e32 v126, 0x11ffe
	v_mov_b32_e32 v128, 0x7060302
	v_cndmask_b32_e32 v126, 0, v126, vcc
	v_add_co_u32_e32 v124, vcc, v124, v126
	s_nop 1
	v_addc_co_u32_e32 v125, vcc, 0, v125, vcc
	s_mov_b32 vcc_lo, 0xaaaaaaaa
	s_mov_b32 vcc_hi, 0xaaaaaaaa
	v_mov_b32_dpp v126, v132 quad_perm:[1,0,3,2] row_mask:0xf bank_mask:0xf
	v_mov_b32_dpp v127, v136 quad_perm:[1,0,3,2] row_mask:0xf bank_mask:0xf
	s_nop 1
	v_cndmask_b32_e32 v127, v132, v127, vcc
	v_cndmask_b32_e32 v126, v126, v136, vcc
	v_perm_b32 v126, v126, v127, v128
	global_store_dword v[124:125], v126, off
	v_add_co_u32_e32 v124, vcc, 0x1200, v124
	s_nop 1
	v_addc_co_u32_e32 v125, vcc, 0, v125, vcc
	s_mov_b32 vcc_lo, 0xaaaaaaaa
	s_mov_b32 vcc_hi, 0xaaaaaaaa
	v_mov_b32_dpp v126, v133 quad_perm:[1,0,3,2] row_mask:0xf bank_mask:0xf
	v_mov_b32_dpp v127, v137 quad_perm:[1,0,3,2] row_mask:0xf bank_mask:0xf
	s_nop 1
	v_cndmask_b32_e32 v127, v133, v127, vcc
	v_cndmask_b32_e32 v126, v126, v137, vcc
	v_perm_b32 v126, v126, v127, v128
	global_store_dword v[124:125], v126, off
	v_add_co_u32_e32 v124, vcc, 0x1200, v124
	s_nop 1
	v_addc_co_u32_e32 v125, vcc, 0, v125, vcc
	s_mov_b32 vcc_lo, 0xaaaaaaaa
	s_mov_b32 vcc_hi, 0xaaaaaaaa
	v_mov_b32_dpp v126, v134 quad_perm:[1,0,3,2] row_mask:0xf bank_mask:0xf
	v_mov_b32_dpp v127, v138 quad_perm:[1,0,3,2] row_mask:0xf bank_mask:0xf
	s_nop 1
	v_cndmask_b32_e32 v127, v134, v127, vcc
	v_cndmask_b32_e32 v126, v126, v138, vcc
	v_perm_b32 v126, v126, v127, v128
	global_store_dword v[124:125], v126, off
	v_add_co_u32_e32 v124, vcc, 0x1200, v124
	s_nop 1
	v_addc_co_u32_e32 v125, vcc, 0, v125, vcc
	s_mov_b32 vcc_lo, 0xaaaaaaaa
	s_mov_b32 vcc_hi, 0xaaaaaaaa
	v_mov_b32_dpp v126, v135 quad_perm:[1,0,3,2] row_mask:0xf bank_mask:0xf
	v_mov_b32_dpp v127, v139 quad_perm:[1,0,3,2] row_mask:0xf bank_mask:0xf
	s_nop 1
	v_cndmask_b32_e32 v127, v135, v127, vcc
	v_cndmask_b32_e32 v126, v126, v139, vcc
	v_perm_b32 v126, v126, v127, v128
	global_store_dword v[124:125], v126, off

; __device__ __forceinline__ bfu f2bf(float f) {
;   unsigned u = __float_as_uint(f);
;   u += 0x7fffu + ((u >> 16) & 1u);
;   return (bfu)(u >> 16);
; }
;   __device__ __forceinline__ void operator()(const f32x4 (&acc)[2][2][4][2], const Unit& u, int wr, int wc, int fr, int fq) const {
;     ...
;           } else if (sec == 11) {
;             const int t = tbase + rl;
;             bfu* dst = vt + ((size_t)bb * 512 + (c0 - 5632)) * TPB + t;
; #pragma unroll
;             for (int j = 0; j < 4; ++j) {
;               dst[(size_t)j * TPB] = f2bf(v0[j]);
;               dst[(size_t)(16 + j) * TPB] = f2bf(v1[j]);
;             }
.LBB0_404:
	s_andn2_b64 vcc, exec, s[2:3]
	s_cbranch_vccnz .LBB0_406
	v_readlane_b32 s2, v252, 45
	v_readlane_b32 s3, v252, 46
	s_ashr_i32 s21, s20, 31
	v_lshl_add_u64 v[118:119], s[20:21], 0, v[156:157]
	v_lshl_add_u64 v[116:117], s[2:3], 0, v[170:171]
	v_lshl_add_u64 v[116:117], v[118:119], 1, v[116:117]
	v_bfe_u32 v118, v124, 16, 1
	v_add3_u32 v124, v124, v118, s94
	v_bfe_u32 v118, v125, 16, 1
	v_add3_u32 v125, v125, v118, s94
	v_bfe_u32 v118, v126, 16, 1
	v_add3_u32 v126, v126, v118, s94
	v_bfe_u32 v118, v127, 16, 1
	v_add3_u32 v127, v127, v118, s94
	v_bfe_u32 v118, v128, 16, 1
	v_add3_u32 v128, v128, v118, s94
	v_bfe_u32 v118, v129, 16, 1
	v_add3_u32 v129, v129, v118, s94
	v_bfe_u32 v118, v130, 16, 1
	v_add3_u32 v130, v130, v118, s94
	v_bfe_u32 v118, v131, 16, 1
	v_add3_u32 v131, v131, v118, s94
	s_mov_b32 vcc_lo, 0xaaaaaaaa
	s_mov_b32 vcc_hi, 0xaaaaaaaa
	v_mov_b32_e32 v118, 0x11ffe
	v_mov_b32_e32 v120, 0x7060302
	v_cndmask_b32_e32 v118, 0, v118, vcc
	v_add_co_u32_e32 v116, vcc, v116, v118
	s_nop 1
	v_addc_co_u32_e32 v117, vcc, 0, v117, vcc
	s_mov_b32 vcc_lo, 0xaaaaaaaa
	s_mov_b32 vcc_hi, 0xaaaaaaaa
	v_mov_b32_dpp v118, v124 quad_perm:[1,0,3,2] row_mask:0xf bank_mask:0xf
	v_mov_b32_dpp v119, v128 quad_perm:[1,0,3,2] row_mask:0xf bank_mask:0xf
	s_nop 1
	v_cndmask_b32_e32 v119, v124, v119, vcc
	v_cndmask_b32_e32 v118, v118, v128, vcc
	v_perm_b32 v118, v118, v119, v120
	global_store_dword v[116:117], v118, off offset:32
	v_add_co_u32_e32 v116, vcc, 0x1200, v116
	s_nop 1
	v_addc_co_u32_e32 v117, vcc, 0, v117, vcc
	s_mov_b32 vcc_lo, 0xaaaaaaaa
	s_mov_b32 vcc_hi, 0xaaaaaaaa
	v_mov_b32_dpp v118, v125 quad_perm:[1,0,3,2] row_mask:0xf bank_mask:0xf
	v_mov_b32_dpp v119, v129 quad_perm:[1,0,3,2] row_mask:0xf bank_mask:0xf
	s_nop 1
	v_cndmask_b32_e32 v119, v125, v119, vcc
	v_cndmask_b32_e32 v118, v118, v129, vcc
	v_perm_b32 v118, v118, v119, v120
	global_store_dword v[116:117], v118, off offset:32
	v_add_co_u32_e32 v116, vcc, 0x1200, v116
	s_nop 1
	v_addc_co_u32_e32 v117, vcc, 0, v117, vcc
	s_mov_b32 vcc_lo, 0xaaaaaaaa
	s_mov_b32 vcc_hi, 0xaaaaaaaa
	v_mov_b32_dpp v118, v126 quad_perm:[1,0,3,2] row_mask:0xf bank_mask:0xf
	v_mov_b32_dpp v119, v130 quad_perm:[1,0,3,2] row_mask:0xf bank_mask:0xf
	s_nop 1
	v_cndmask_b32_e32 v119, v126, v119, vcc
	v_cndmask_b32_e32 v118, v118, v130, vcc
	v_perm_b32 v118, v118, v119, v120
	global_store_dword v[116:117], v118, off offset:32
	v_add_co_u32_e32 v116, vcc, 0x1200, v116
	s_nop 1
	v_addc_co_u32_e32 v117, vcc, 0, v117, vcc
	s_mov_b32 vcc_lo, 0xaaaaaaaa
	s_mov_b32 vcc_hi, 0xaaaaaaaa
	v_mov_b32_dpp v118, v127 quad_perm:[1,0,3,2] row_mask:0xf bank_mask:0xf
	v_mov_b32_dpp v119, v131 quad_perm:[1,0,3,2] row_mask:0xf bank_mask:0xf
	s_nop 1
	v_cndmask_b32_e32 v119, v127, v119, vcc
	v_cndmask_b32_e32 v118, v118, v131, vcc
	v_perm_b32 v118, v118, v119, v120
	global_store_dword v[116:117], v118, off offset:32

; __device__ __forceinline__ bfu f2bf(float f) {
;   unsigned u = __float_as_uint(f);
;   u += 0x7fffu + ((u >> 16) & 1u);
;   return (bfu)(u >> 16);
; }
;   __device__ __forceinline__ void operator()(const f32x4 (&acc)[2][2][4][2], const Unit& u, int wr, int wc, int fr, int fq) const {
;     ...
;           } else if (sec == 11) {
;             const int t = tbase + rl;
;             bfu* dst = vt + ((size_t)bb * 512 + (c0 - 5632)) * TPB + t;
; #pragma unroll
;             for (int j = 0; j < 4; ++j) {
;               dst[(size_t)j * TPB] = f2bf(v0[j]);
;               dst[(size_t)(16 + j) * TPB] = f2bf(v1[j]);
;             }
.LBB0_428:
	s_andn2_b64 vcc, exec, s[2:3]
	s_cbranch_vccnz .LBB0_430
	v_readlane_b32 s2, v252, 45
	v_readlane_b32 s3, v252, 46
	s_ashr_i32 s21, s20, 31
	v_lshl_add_u64 v[110:111], s[20:21], 0, v[156:157]
	v_lshl_add_u64 v[108:109], s[2:3], 0, v[170:171]
	v_lshl_add_u64 v[108:109], v[110:111], 1, v[108:109]
	v_bfe_u32 v110, v116, 16, 1
	v_add3_u32 v116, v116, v110, s94
	v_bfe_u32 v110, v117, 16, 1
	v_add3_u32 v117, v117, v110, s94
	v_bfe_u32 v110, v118, 16, 1
	v_add3_u32 v118, v118, v110, s94
	v_bfe_u32 v110, v119, 16, 1
	v_add3_u32 v119, v119, v110, s94
	v_bfe_u32 v110, v120, 16, 1
	v_add3_u32 v120, v120, v110, s94
	v_bfe_u32 v110, v121, 16, 1
	v_add3_u32 v121, v121, v110, s94
	v_bfe_u32 v110, v122, 16, 1
	v_add3_u32 v122, v122, v110, s94
	v_bfe_u32 v110, v123, 16, 1
	v_add3_u32 v123, v123, v110, s94
	s_mov_b32 vcc_lo, 0xaaaaaaaa
	s_mov_b32 vcc_hi, 0xaaaaaaaa
	v_mov_b32_e32 v110, 0x11ffe
	v_mov_b32_e32 v112, 0x7060302
	v_cndmask_b32_e32 v110, 0, v110, vcc
	v_add_co_u32_e32 v108, vcc, v108, v110
	s_nop 1
	v_addc_co_u32_e32 v109, vcc, 0, v109, vcc
	s_mov_b32 vcc_lo, 0xaaaaaaaa
	s_mov_b32 vcc_hi, 0xaaaaaaaa
	v_mov_b32_dpp v110, v116 quad_perm:[1,0,3,2] row_mask:0xf bank_mask:0xf
	v_mov_b32_dpp v111, v120 quad_perm:[1,0,3,2] row_mask:0xf bank_mask:0xf
	s_nop 1
	v_cndmask_b32_e32 v111, v116, v111, vcc
	v_cndmask_b32_e32 v110, v110, v120, vcc
	v_perm_b32 v110, v110, v111, v112
	global_store_dword v[108:109], v110, off offset:64
	v_add_co_u32_e32 v108, vcc, 0x1200, v108
	s_nop 1
	v_addc_co_u32_e32 v109, vcc, 0, v109, vcc
	s_mov_b32 vcc_lo, 0xaaaaaaaa
	s_mov_b32 vcc_hi, 0xaaaaaaaa
	v_mov_b32_dpp v110, v117 quad_perm:[1,0,3,2] row_mask:0xf bank_mask:0xf
	v_mov_b32_dpp v111, v121 quad_perm:[1,0,3,2] row_mask:0xf bank_mask:0xf
	s_nop 1
	v_cndmask_b32_e32 v111, v117, v111, vcc
	v_cndmask_b32_e32 v110, v110, v121, vcc
	v_perm_b32 v110, v110, v111, v112
	global_store_dword v[108:109], v110, off offset:64
	v_add_co_u32_e32 v108, vcc, 0x1200, v108
	s_nop 1
	v_addc_co_u32_e32 v109, vcc, 0, v109, vcc
	s_mov_b32 vcc_lo, 0xaaaaaaaa
	s_mov_b32 vcc_hi, 0xaaaaaaaa
	v_mov_b32_dpp v110, v118 quad_perm:[1,0,3,2] row_mask:0xf bank_mask:0xf
	v_mov_b32_dpp v111, v122 quad_perm:[1,0,3,2] row_mask:0xf bank_mask:0xf
	s_nop 1
	v_cndmask_b32_e32 v111, v118, v111, vcc
	v_cndmask_b32_e32 v110, v110, v122, vcc
	v_perm_b32 v110, v110, v111, v112
	global_store_dword v[108:109], v110, off offset:64
	v_add_co_u32_e32 v108, vcc, 0x1200, v108
	s_nop 1
	v_addc_co_u32_e32 v109, vcc, 0, v109, vcc
	s_mov_b32 vcc_lo, 0xaaaaaaaa
	s_mov_b32 vcc_hi, 0xaaaaaaaa
	v_mov_b32_dpp v110, v119 quad_perm:[1,0,3,2] row_mask:0xf bank_mask:0xf
	v_mov_b32_dpp v111, v123 quad_perm:[1,0,3,2] row_mask:0xf bank_mask:0xf
	s_nop 1
	v_cndmask_b32_e32 v111, v119, v111, vcc
	v_cndmask_b32_e32 v110, v110, v123, vcc
	v_perm_b32 v110, v110, v111, v112
	global_store_dword v[108:109], v110, off offset:64

; __device__ __forceinline__ bfu f2bf(float f) {
;   unsigned u = __float_as_uint(f);
;   u += 0x7fffu + ((u >> 16) & 1u);
;   return (bfu)(u >> 16);
; }
;   __device__ __forceinline__ void operator()(const f32x4 (&acc)[2][2][4][2], const Unit& u, int wr, int wc, int fr, int fq) const {
;     ...
;           } else if (sec == 11) {
;             const int t = tbase + rl;
;             bfu* dst = vt + ((size_t)bb * 512 + (c0 - 5632)) * TPB + t;
; #pragma unroll
;             for (int j = 0; j < 4; ++j) {
;               dst[(size_t)j * TPB] = f2bf(v0[j]);
;               dst[(size_t)(16 + j) * TPB] = f2bf(v1[j]);
;             }
.LBB0_454:
	s_andn2_b64 vcc, exec, s[2:3]
	s_cbranch_vccnz .LBB0_456
	v_readlane_b32 s2, v252, 45
	v_readlane_b32 s3, v252, 46
	s_ashr_i32 s21, s20, 31
	v_lshl_add_u64 v[102:103], s[20:21], 0, v[156:157]
	v_lshl_add_u64 v[100:101], s[2:3], 0, v[170:171]
	v_lshl_add_u64 v[100:101], v[102:103], 1, v[100:101]
	v_bfe_u32 v102, v108, 16, 1
	v_add3_u32 v108, v108, v102, s94
	v_bfe_u32 v102, v109, 16, 1
	v_add3_u32 v109, v109, v102, s94
	v_bfe_u32 v102, v110, 16, 1
	v_add3_u32 v110, v110, v102, s94
	v_bfe_u32 v102, v111, 16, 1
	v_add3_u32 v111, v111, v102, s94
	v_bfe_u32 v102, v112, 16, 1
	v_add3_u32 v112, v112, v102, s94
	v_bfe_u32 v102, v113, 16, 1
	v_add3_u32 v113, v113, v102, s94
	v_bfe_u32 v102, v114, 16, 1
	v_add3_u32 v114, v114, v102, s94
	v_bfe_u32 v102, v115, 16, 1
	v_add3_u32 v115, v115, v102, s94
	s_mov_b32 vcc_lo, 0xaaaaaaaa
	s_mov_b32 vcc_hi, 0xaaaaaaaa
	v_mov_b32_e32 v102, 0x11ffe
	v_mov_b32_e32 v104, 0x7060302
	v_cndmask_b32_e32 v102, 0, v102, vcc
	v_add_co_u32_e32 v100, vcc, v100, v102
	s_nop 1
	v_addc_co_u32_e32 v101, vcc, 0, v101, vcc
	s_mov_b32 vcc_lo, 0xaaaaaaaa
	s_mov_b32 vcc_hi, 0xaaaaaaaa
	v_mov_b32_dpp v102, v108 quad_perm:[1,0,3,2] row_mask:0xf bank_mask:0xf
	v_mov_b32_dpp v103, v112 quad_perm:[1,0,3,2] row_mask:0xf bank_mask:0xf
	s_nop 1
	v_cndmask_b32_e32 v103, v108, v103, vcc
	v_cndmask_b32_e32 v102, v102, v112, vcc
	v_perm_b32 v102, v102, v103, v104
	global_store_dword v[100:101], v102, off offset:96
	v_add_co_u32_e32 v100, vcc, 0x1200, v100
	s_nop 1
	v_addc_co_u32_e32 v101, vcc, 0, v101, vcc
	s_mov_b32 vcc_lo, 0xaaaaaaaa
	s_mov_b32 vcc_hi, 0xaaaaaaaa
	v_mov_b32_dpp v102, v109 quad_perm:[1,0,3,2] row_mask:0xf bank_mask:0xf
	v_mov_b32_dpp v103, v113 quad_perm:[1,0,3,2] row_mask:0xf bank_mask:0xf
	s_nop 1
	v_cndmask_b32_e32 v103, v109, v103, vcc
	v_cndmask_b32_e32 v102, v102, v113, vcc
	v_perm_b32 v102, v102, v103, v104
	global_store_dword v[100:101], v102, off offset:96
	v_add_co_u32_e32 v100, vcc, 0x1200, v100
	s_nop 1
	v_addc_co_u32_e32 v101, vcc, 0, v101, vcc
	s_mov_b32 vcc_lo, 0xaaaaaaaa
	s_mov_b32 vcc_hi, 0xaaaaaaaa
	v_mov_b32_dpp v102, v110 quad_perm:[1,0,3,2] row_mask:0xf bank_mask:0xf
	v_mov_b32_dpp v103, v114 quad_perm:[1,0,3,2] row_mask:0xf bank_mask:0xf
	s_nop 1
	v_cndmask_b32_e32 v103, v110, v103, vcc
	v_cndmask_b32_e32 v102, v102, v114, vcc
	v_perm_b32 v102, v102, v103, v104
	global_store_dword v[100:101], v102, off offset:96
	v_add_co_u32_e32 v100, vcc, 0x1200, v100
	s_nop 1
	v_addc_co_u32_e32 v101, vcc, 0, v101, vcc
	s_mov_b32 vcc_lo, 0xaaaaaaaa
	s_mov_b32 vcc_hi, 0xaaaaaaaa
	v_mov_b32_dpp v102, v111 quad_perm:[1,0,3,2] row_mask:0xf bank_mask:0xf
	v_mov_b32_dpp v103, v115 quad_perm:[1,0,3,2] row_mask:0xf bank_mask:0xf
	s_nop 1
	v_cndmask_b32_e32 v103, v111, v103, vcc
	v_cndmask_b32_e32 v102, v102, v115, vcc
	v_perm_b32 v102, v102, v103, v104
	global_store_dword v[100:101], v102, off offset:96

; __device__ __forceinline__ bfu f2bf(float f) {
;   unsigned u = __float_as_uint(f);
;   u += 0x7fffu + ((u >> 16) & 1u);
;   return (bfu)(u >> 16);
; }
;   __device__ __forceinline__ void operator()(const f32x4 (&acc)[2][2][4][2], const Unit& u, int wr, int wc, int fr, int fq) const {
;     ...
;           } else if (sec == 11) {
;             const int t = tbase + rl;
;             bfu* dst = vt + ((size_t)bb * 512 + (c0 - 5632)) * TPB + t;
; #pragma unroll
;             for (int j = 0; j < 4; ++j) {
;               dst[(size_t)j * TPB] = f2bf(v0[j]);
;               dst[(size_t)(16 + j) * TPB] = f2bf(v1[j]);
;             }
.LBB0_480:
	s_andn2_b64 vcc, exec, s[2:3]
	s_cbranch_vccnz .LBB0_482
	v_readlane_b32 s2, v252, 45
	v_readlane_b32 s3, v252, 46
	s_ashr_i32 s21, s20, 31
	v_lshl_add_u64 v[94:95], s[20:21], 0, v[156:157]
	v_lshl_add_u64 v[92:93], s[2:3], 0, v[170:171]
	v_lshl_add_u64 v[92:93], v[94:95], 1, v[92:93]
	v_bfe_u32 v94, v100, 16, 1
	v_add3_u32 v100, v100, v94, s94
	v_bfe_u32 v94, v101, 16, 1
	v_add3_u32 v101, v101, v94, s94
	v_bfe_u32 v94, v102, 16, 1
	v_add3_u32 v102, v102, v94, s94
	v_bfe_u32 v94, v103, 16, 1
	v_add3_u32 v103, v103, v94, s94
	v_bfe_u32 v94, v104, 16, 1
	v_add3_u32 v104, v104, v94, s94
	v_bfe_u32 v94, v105, 16, 1
	v_add3_u32 v105, v105, v94, s94
	v_bfe_u32 v94, v106, 16, 1
	v_add3_u32 v106, v106, v94, s94
	v_bfe_u32 v94, v107, 16, 1
	v_add3_u32 v107, v107, v94, s94
	s_mov_b32 vcc_lo, 0xaaaaaaaa
	s_mov_b32 vcc_hi, 0xaaaaaaaa
	v_mov_b32_e32 v94, 0x11ffe
	v_mov_b32_e32 v96, 0x7060302
	v_cndmask_b32_e32 v94, 0, v94, vcc
	v_add_co_u32_e32 v92, vcc, v92, v94
	s_nop 1
	v_addc_co_u32_e32 v93, vcc, 0, v93, vcc
	s_mov_b32 vcc_lo, 0xaaaaaaaa
	s_mov_b32 vcc_hi, 0xaaaaaaaa
	v_mov_b32_dpp v94, v100 quad_perm:[1,0,3,2] row_mask:0xf bank_mask:0xf
	v_mov_b32_dpp v95, v104 quad_perm:[1,0,3,2] row_mask:0xf bank_mask:0xf
	s_nop 1
	v_cndmask_b32_e32 v95, v100, v95, vcc
	v_cndmask_b32_e32 v94, v94, v104, vcc
	v_perm_b32 v94, v94, v95, v96
	global_store_dword v[92:93], v94, off offset:256
	v_add_co_u32_e32 v92, vcc, 0x1200, v92
	s_nop 1
	v_addc_co_u32_e32 v93, vcc, 0, v93, vcc
	s_mov_b32 vcc_lo, 0xaaaaaaaa
	s_mov_b32 vcc_hi, 0xaaaaaaaa
	v_mov_b32_dpp v94, v101 quad_perm:[1,0,3,2] row_mask:0xf bank_mask:0xf
	v_mov_b32_dpp v95, v105 quad_perm:[1,0,3,2] row_mask:0xf bank_mask:0xf
	s_nop 1
	v_cndmask_b32_e32 v95, v101, v95, vcc
	v_cndmask_b32_e32 v94, v94, v105, vcc
	v_perm_b32 v94, v94, v95, v96
	global_store_dword v[92:93], v94, off offset:256
	v_add_co_u32_e32 v92, vcc, 0x1200, v92
	s_nop 1
	v_addc_co_u32_e32 v93, vcc, 0, v93, vcc
	s_mov_b32 vcc_lo, 0xaaaaaaaa
	s_mov_b32 vcc_hi, 0xaaaaaaaa
	v_mov_b32_dpp v94, v102 quad_perm:[1,0,3,2] row_mask:0xf bank_mask:0xf
	v_mov_b32_dpp v95, v106 quad_perm:[1,0,3,2] row_mask:0xf bank_mask:0xf
	s_nop 1
	v_cndmask_b32_e32 v95, v102, v95, vcc
	v_cndmask_b32_e32 v94, v94, v106, vcc
	v_perm_b32 v94, v94, v95, v96
	global_store_dword v[92:93], v94, off offset:256
	v_add_co_u32_e32 v92, vcc, 0x1200, v92
	s_nop 1
	v_addc_co_u32_e32 v93, vcc, 0, v93, vcc
	s_mov_b32 vcc_lo, 0xaaaaaaaa
	s_mov_b32 vcc_hi, 0xaaaaaaaa
	v_mov_b32_dpp v94, v103 quad_perm:[1,0,3,2] row_mask:0xf bank_mask:0xf
	v_mov_b32_dpp v95, v107 quad_perm:[1,0,3,2] row_mask:0xf bank_mask:0xf
	s_nop 1
	v_cndmask_b32_e32 v95, v103, v95, vcc
	v_cndmask_b32_e32 v94, v94, v107, vcc
	v_perm_b32 v94, v94, v95, v96
	global_store_dword v[92:93], v94, off offset:256

; __device__ __forceinline__ bfu f2bf(float f) {
;   unsigned u = __float_as_uint(f);
;   u += 0x7fffu + ((u >> 16) & 1u);
;   return (bfu)(u >> 16);
; }
;   __device__ __forceinline__ void operator()(const f32x4 (&acc)[2][2][4][2], const Unit& u, int wr, int wc, int fr, int fq) const {
;     ...
;           } else if (sec == 11) {
;             const int t = tbase + rl;
;             bfu* dst = vt + ((size_t)bb * 512 + (c0 - 5632)) * TPB + t;
; #pragma unroll
;             for (int j = 0; j < 4; ++j) {
;               dst[(size_t)j * TPB] = f2bf(v0[j]);
;               dst[(size_t)(16 + j) * TPB] = f2bf(v1[j]);
;             }
.LBB0_506:
	s_andn2_b64 vcc, exec, s[2:3]
	s_cbranch_vccnz .LBB0_508
	v_readlane_b32 s2, v252, 45
	v_readlane_b32 s3, v252, 46
	s_ashr_i32 s21, s20, 31
	v_lshl_add_u64 v[86:87], s[20:21], 0, v[156:157]
	v_lshl_add_u64 v[84:85], s[2:3], 0, v[170:171]
	v_lshl_add_u64 v[84:85], v[86:87], 1, v[84:85]
	v_bfe_u32 v86, v92, 16, 1
	v_add3_u32 v92, v92, v86, s94
	v_bfe_u32 v86, v93, 16, 1
	v_add3_u32 v93, v93, v86, s94
	v_bfe_u32 v86, v94, 16, 1
	v_add3_u32 v94, v94, v86, s94
	v_bfe_u32 v86, v95, 16, 1
	v_add3_u32 v95, v95, v86, s94
	v_bfe_u32 v86, v96, 16, 1
	v_add3_u32 v96, v96, v86, s94
	v_bfe_u32 v86, v97, 16, 1
	v_add3_u32 v97, v97, v86, s94
	v_bfe_u32 v86, v98, 16, 1
	v_add3_u32 v98, v98, v86, s94
	v_bfe_u32 v86, v99, 16, 1
	v_add3_u32 v99, v99, v86, s94
	s_mov_b32 vcc_lo, 0xaaaaaaaa
	s_mov_b32 vcc_hi, 0xaaaaaaaa
	v_mov_b32_e32 v86, 0x11ffe
	v_mov_b32_e32 v88, 0x7060302
	v_cndmask_b32_e32 v86, 0, v86, vcc
	v_add_co_u32_e32 v84, vcc, v84, v86
	s_nop 1
	v_addc_co_u32_e32 v85, vcc, 0, v85, vcc
	s_mov_b32 vcc_lo, 0xaaaaaaaa
	s_mov_b32 vcc_hi, 0xaaaaaaaa
	v_mov_b32_dpp v86, v92 quad_perm:[1,0,3,2] row_mask:0xf bank_mask:0xf
	v_mov_b32_dpp v87, v96 quad_perm:[1,0,3,2] row_mask:0xf bank_mask:0xf
	s_nop 1
	v_cndmask_b32_e32 v87, v92, v87, vcc
	v_cndmask_b32_e32 v86, v86, v96, vcc
	v_perm_b32 v86, v86, v87, v88
	global_store_dword v[84:85], v86, off offset:288
	v_add_co_u32_e32 v84, vcc, 0x1200, v84
	s_nop 1
	v_addc_co_u32_e32 v85, vcc, 0, v85, vcc
	s_mov_b32 vcc_lo, 0xaaaaaaaa
	s_mov_b32 vcc_hi, 0xaaaaaaaa
	v_mov_b32_dpp v86, v93 quad_perm:[1,0,3,2] row_mask:0xf bank_mask:0xf
	v_mov_b32_dpp v87, v97 quad_perm:[1,0,3,2] row_mask:0xf bank_mask:0xf
	s_nop 1
	v_cndmask_b32_e32 v87, v93, v87, vcc
	v_cndmask_b32_e32 v86, v86, v97, vcc
	v_perm_b32 v86, v86, v87, v88
	global_store_dword v[84:85], v86, off offset:288
	v_add_co_u32_e32 v84, vcc, 0x1200, v84
	s_nop 1
	v_addc_co_u32_e32 v85, vcc, 0, v85, vcc
	s_mov_b32 vcc_lo, 0xaaaaaaaa
	s_mov_b32 vcc_hi, 0xaaaaaaaa
	v_mov_b32_dpp v86, v94 quad_perm:[1,0,3,2] row_mask:0xf bank_mask:0xf
	v_mov_b32_dpp v87, v98 quad_perm:[1,0,3,2] row_mask:0xf bank_mask:0xf
	s_nop 1
	v_cndmask_b32_e32 v87, v94, v87, vcc
	v_cndmask_b32_e32 v86, v86, v98, vcc
	v_perm_b32 v86, v86, v87, v88
	global_store_dword v[84:85], v86, off offset:288
	v_add_co_u32_e32 v84, vcc, 0x1200, v84
	s_nop 1
	v_addc_co_u32_e32 v85, vcc, 0, v85, vcc
	s_mov_b32 vcc_lo, 0xaaaaaaaa
	s_mov_b32 vcc_hi, 0xaaaaaaaa
	v_mov_b32_dpp v86, v95 quad_perm:[1,0,3,2] row_mask:0xf bank_mask:0xf
	v_mov_b32_dpp v87, v99 quad_perm:[1,0,3,2] row_mask:0xf bank_mask:0xf
	s_nop 1
	v_cndmask_b32_e32 v87, v95, v87, vcc
	v_cndmask_b32_e32 v86, v86, v99, vcc
	v_perm_b32 v86, v86, v87, v88
	global_store_dword v[84:85], v86, off offset:288

; __device__ __forceinline__ bfu f2bf(float f) {
;   unsigned u = __float_as_uint(f);
;   u += 0x7fffu + ((u >> 16) & 1u);
;   return (bfu)(u >> 16);
; }
;   __device__ __forceinline__ void operator()(const f32x4 (&acc)[2][2][4][2], const Unit& u, int wr, int wc, int fr, int fq) const {
;     ...
;           } else if (sec == 11) {
;             const int t = tbase + rl;
;             bfu* dst = vt + ((size_t)bb * 512 + (c0 - 5632)) * TPB + t;
; #pragma unroll
;             for (int j = 0; j < 4; ++j) {
;               dst[(size_t)j * TPB] = f2bf(v0[j]);
;               dst[(size_t)(16 + j) * TPB] = f2bf(v1[j]);
;             }
.LBB0_532:
	s_andn2_b64 vcc, exec, s[2:3]
	s_cbranch_vccnz .LBB0_534
	v_readlane_b32 s2, v252, 45
	v_readlane_b32 s3, v252, 46
	s_ashr_i32 s21, s20, 31
	v_lshl_add_u64 v[78:79], s[20:21], 0, v[156:157]
	v_lshl_add_u64 v[76:77], s[2:3], 0, v[170:171]
	v_lshl_add_u64 v[76:77], v[78:79], 1, v[76:77]
	v_bfe_u32 v78, v84, 16, 1
	v_add3_u32 v84, v84, v78, s94
	v_bfe_u32 v78, v85, 16, 1
	v_add3_u32 v85, v85, v78, s94
	v_bfe_u32 v78, v86, 16, 1
	v_add3_u32 v86, v86, v78, s94
	v_bfe_u32 v78, v87, 16, 1
	v_add3_u32 v87, v87, v78, s94
	v_bfe_u32 v78, v88, 16, 1
	v_add3_u32 v88, v88, v78, s94
	v_bfe_u32 v78, v89, 16, 1
	v_add3_u32 v89, v89, v78, s94
	v_bfe_u32 v78, v90, 16, 1
	v_add3_u32 v90, v90, v78, s94
	v_bfe_u32 v78, v91, 16, 1
	v_add3_u32 v91, v91, v78, s94
	s_mov_b32 vcc_lo, 0xaaaaaaaa
	s_mov_b32 vcc_hi, 0xaaaaaaaa
	v_mov_b32_e32 v78, 0x11ffe
	v_mov_b32_e32 v80, 0x7060302
	v_cndmask_b32_e32 v78, 0, v78, vcc
	v_add_co_u32_e32 v76, vcc, v76, v78
	s_nop 1
	v_addc_co_u32_e32 v77, vcc, 0, v77, vcc
	s_mov_b32 vcc_lo, 0xaaaaaaaa
	s_mov_b32 vcc_hi, 0xaaaaaaaa
	v_mov_b32_dpp v78, v84 quad_perm:[1,0,3,2] row_mask:0xf bank_mask:0xf
	v_mov_b32_dpp v79, v88 quad_perm:[1,0,3,2] row_mask:0xf bank_mask:0xf
	s_nop 1
	v_cndmask_b32_e32 v79, v84, v79, vcc
	v_cndmask_b32_e32 v78, v78, v88, vcc
	v_perm_b32 v78, v78, v79, v80
	global_store_dword v[76:77], v78, off offset:320
	v_add_co_u32_e32 v76, vcc, 0x1200, v76
	s_nop 1
	v_addc_co_u32_e32 v77, vcc, 0, v77, vcc
	s_mov_b32 vcc_lo, 0xaaaaaaaa
	s_mov_b32 vcc_hi, 0xaaaaaaaa
	v_mov_b32_dpp v78, v85 quad_perm:[1,0,3,2] row_mask:0xf bank_mask:0xf
	v_mov_b32_dpp v79, v89 quad_perm:[1,0,3,2] row_mask:0xf bank_mask:0xf
	s_nop 1
	v_cndmask_b32_e32 v79, v85, v79, vcc
	v_cndmask_b32_e32 v78, v78, v89, vcc
	v_perm_b32 v78, v78, v79, v80
	global_store_dword v[76:77], v78, off offset:320
	v_add_co_u32_e32 v76, vcc, 0x1200, v76
	s_nop 1
	v_addc_co_u32_e32 v77, vcc, 0, v77, vcc
	s_mov_b32 vcc_lo, 0xaaaaaaaa
	s_mov_b32 vcc_hi, 0xaaaaaaaa
	v_mov_b32_dpp v78, v86 quad_perm:[1,0,3,2] row_mask:0xf bank_mask:0xf
	v_mov_b32_dpp v79, v90 quad_perm:[1,0,3,2] row_mask:0xf bank_mask:0xf
	s_nop 1
	v_cndmask_b32_e32 v79, v86, v79, vcc
	v_cndmask_b32_e32 v78, v78, v90, vcc
	v_perm_b32 v78, v78, v79, v80
	global_store_dword v[76:77], v78, off offset:320
	v_add_co_u32_e32 v76, vcc, 0x1200, v76
	s_nop 1
	v_addc_co_u32_e32 v77, vcc, 0, v77, vcc
	s_mov_b32 vcc_lo, 0xaaaaaaaa
	s_mov_b32 vcc_hi, 0xaaaaaaaa
	v_mov_b32_dpp v78, v87 quad_perm:[1,0,3,2] row_mask:0xf bank_mask:0xf
	v_mov_b32_dpp v79, v91 quad_perm:[1,0,3,2] row_mask:0xf bank_mask:0xf
	s_nop 1
	v_cndmask_b32_e32 v79, v87, v79, vcc
	v_cndmask_b32_e32 v78, v78, v91, vcc
	v_perm_b32 v78, v78, v79, v80
	global_store_dword v[76:77], v78, off offset:320

; __device__ __forceinline__ bfu f2bf(float f) {
;   unsigned u = __float_as_uint(f);
;   u += 0x7fffu + ((u >> 16) & 1u);
;   return (bfu)(u >> 16);
; }
;   __device__ __forceinline__ void operator()(const f32x4 (&acc)[2][2][4][2], const Unit& u, int wr, int wc, int fr, int fq) const {
;     ...
;           } else if (sec == 11) {
;             const int t = tbase + rl;
;             bfu* dst = vt + ((size_t)bb * 512 + (c0 - 5632)) * TPB + t;
; #pragma unroll
;             for (int j = 0; j < 4; ++j) {
;               dst[(size_t)j * TPB] = f2bf(v0[j]);
;               dst[(size_t)(16 + j) * TPB] = f2bf(v1[j]);
;             }
.LBB0_558:
	s_andn2_b64 vcc, exec, s[2:3]
	s_cbranch_vccnz .LBB0_560
	v_readlane_b32 s2, v252, 45
	v_readlane_b32 s3, v252, 46
	s_ashr_i32 s21, s20, 31
	v_lshl_add_u64 v[70:71], s[20:21], 0, v[156:157]
	v_lshl_add_u64 v[68:69], s[2:3], 0, v[170:171]
	v_lshl_add_u64 v[68:69], v[70:71], 1, v[68:69]
	v_bfe_u32 v70, v76, 16, 1
	v_add3_u32 v76, v76, v70, s94
	v_bfe_u32 v70, v77, 16, 1
	v_add3_u32 v77, v77, v70, s94
	v_bfe_u32 v70, v78, 16, 1
	v_add3_u32 v78, v78, v70, s94
	v_bfe_u32 v70, v79, 16, 1
	v_add3_u32 v79, v79, v70, s94
	v_bfe_u32 v70, v80, 16, 1
	v_add3_u32 v80, v80, v70, s94
	v_bfe_u32 v70, v81, 16, 1
	v_add3_u32 v81, v81, v70, s94
	v_bfe_u32 v70, v82, 16, 1
	v_add3_u32 v82, v82, v70, s94
	v_bfe_u32 v70, v83, 16, 1
	v_add3_u32 v83, v83, v70, s94
	s_mov_b32 vcc_lo, 0xaaaaaaaa
	s_mov_b32 vcc_hi, 0xaaaaaaaa
	v_mov_b32_e32 v70, 0x11ffe
	v_mov_b32_e32 v72, 0x7060302
	v_cndmask_b32_e32 v70, 0, v70, vcc
	v_add_co_u32_e32 v68, vcc, v68, v70
	s_nop 1
	v_addc_co_u32_e32 v69, vcc, 0, v69, vcc
	s_mov_b32 vcc_lo, 0xaaaaaaaa
	s_mov_b32 vcc_hi, 0xaaaaaaaa
	v_mov_b32_dpp v70, v76 quad_perm:[1,0,3,2] row_mask:0xf bank_mask:0xf
	v_mov_b32_dpp v71, v80 quad_perm:[1,0,3,2] row_mask:0xf bank_mask:0xf
	s_nop 1
	v_cndmask_b32_e32 v71, v76, v71, vcc
	v_cndmask_b32_e32 v70, v70, v80, vcc
	v_perm_b32 v70, v70, v71, v72
	global_store_dword v[68:69], v70, off offset:352
	v_add_co_u32_e32 v68, vcc, 0x1200, v68
	s_nop 1
	v_addc_co_u32_e32 v69, vcc, 0, v69, vcc
	s_mov_b32 vcc_lo, 0xaaaaaaaa
	s_mov_b32 vcc_hi, 0xaaaaaaaa
	v_mov_b32_dpp v70, v77 quad_perm:[1,0,3,2] row_mask:0xf bank_mask:0xf
	v_mov_b32_dpp v71, v81 quad_perm:[1,0,3,2] row_mask:0xf bank_mask:0xf
	s_nop 1
	v_cndmask_b32_e32 v71, v77, v71, vcc
	v_cndmask_b32_e32 v70, v70, v81, vcc
	v_perm_b32 v70, v70, v71, v72
	global_store_dword v[68:69], v70, off offset:352
	v_add_co_u32_e32 v68, vcc, 0x1200, v68
	s_nop 1
	v_addc_co_u32_e32 v69, vcc, 0, v69, vcc
	s_mov_b32 vcc_lo, 0xaaaaaaaa
	s_mov_b32 vcc_hi, 0xaaaaaaaa
	v_mov_b32_dpp v70, v78 quad_perm:[1,0,3,2] row_mask:0xf bank_mask:0xf
	v_mov_b32_dpp v71, v82 quad_perm:[1,0,3,2] row_mask:0xf bank_mask:0xf
	s_nop 1
	v_cndmask_b32_e32 v71, v78, v71, vcc
	v_cndmask_b32_e32 v70, v70, v82, vcc
	v_perm_b32 v70, v70, v71, v72
	global_store_dword v[68:69], v70, off offset:352
	v_add_co_u32_e32 v68, vcc, 0x1200, v68
	s_nop 1
	v_addc_co_u32_e32 v69, vcc, 0, v69, vcc
	s_mov_b32 vcc_lo, 0xaaaaaaaa
	s_mov_b32 vcc_hi, 0xaaaaaaaa
	v_mov_b32_dpp v70, v79 quad_perm:[1,0,3,2] row_mask:0xf bank_mask:0xf
	v_mov_b32_dpp v71, v83 quad_perm:[1,0,3,2] row_mask:0xf bank_mask:0xf
	s_nop 1
	v_cndmask_b32_e32 v71, v79, v71, vcc
	v_cndmask_b32_e32 v70, v70, v83, vcc
	v_perm_b32 v70, v70, v71, v72
	global_store_dword v[68:69], v70, off offset:352

; __device__ __forceinline__ bfu f2bf(float f) {
;   unsigned u = __float_as_uint(f);
;   u += 0x7fffu + ((u >> 16) & 1u);
;   return (bfu)(u >> 16);
; }
;   __device__ __forceinline__ void operator()(const f32x4 (&acc)[2][2][4][2], const Unit& u, int wr, int wc, int fr, int fq) const {
;     ...
;           } else if (sec == 11) {
;             const int t = tbase + rl;
;             bfu* dst = vt + ((size_t)bb * 512 + (c0 - 5632)) * TPB + t;
; #pragma unroll
;             for (int j = 0; j < 4; ++j) {
;               dst[(size_t)j * TPB] = f2bf(v0[j]);
;               dst[(size_t)(16 + j) * TPB] = f2bf(v1[j]);
;             }
.LBB0_588:
	s_andn2_b64 vcc, exec, s[0:1]
	s_cbranch_vccnz .LBB0_590
	v_readlane_b32 s0, v252, 45
	v_add_u32_e32 v60, s20, v156
	v_readlane_b32 s1, v252, 46
	v_ashrrev_i32_e32 v61, 31, v60
	s_nop 0
	v_lshl_add_u64 v[62:63], s[0:1], 0, v[90:91]
	v_lshl_add_u64 v[60:61], v[60:61], 1, v[62:63]
	v_bfe_u32 v62, v68, 16, 1
	v_add3_u32 v68, v68, v62, s94
	v_bfe_u32 v62, v69, 16, 1
	v_add3_u32 v69, v69, v62, s94
	v_bfe_u32 v62, v70, 16, 1
	v_add3_u32 v70, v70, v62, s94
	v_bfe_u32 v62, v71, 16, 1
	v_add3_u32 v71, v71, v62, s94
	v_bfe_u32 v62, v72, 16, 1
	v_add3_u32 v72, v72, v62, s94
	v_bfe_u32 v62, v73, 16, 1
	v_add3_u32 v73, v73, v62, s94
	v_bfe_u32 v62, v74, 16, 1
	v_add3_u32 v74, v74, v62, s94
	v_bfe_u32 v62, v75, 16, 1
	v_add3_u32 v75, v75, v62, s94
	s_mov_b32 vcc_lo, 0xaaaaaaaa
	s_mov_b32 vcc_hi, 0xaaaaaaaa
	v_mov_b32_e32 v62, 0x11ffe
	v_mov_b32_e32 v64, 0x7060302
	v_cndmask_b32_e32 v62, 0, v62, vcc
	v_add_co_u32_e32 v60, vcc, v60, v62
	s_nop 1
	v_addc_co_u32_e32 v61, vcc, 0, v61, vcc
	s_mov_b32 vcc_lo, 0xaaaaaaaa
	s_mov_b32 vcc_hi, 0xaaaaaaaa
	v_mov_b32_dpp v62, v68 quad_perm:[1,0,3,2] row_mask:0xf bank_mask:0xf
	v_mov_b32_dpp v63, v72 quad_perm:[1,0,3,2] row_mask:0xf bank_mask:0xf
	s_nop 1
	v_cndmask_b32_e32 v63, v68, v63, vcc
	v_cndmask_b32_e32 v62, v62, v72, vcc
	v_perm_b32 v62, v62, v63, v64
	global_store_dword v[60:61], v62, off
	v_add_co_u32_e32 v60, vcc, 0x1200, v60
	s_nop 1
	v_addc_co_u32_e32 v61, vcc, 0, v61, vcc
	s_mov_b32 vcc_lo, 0xaaaaaaaa
	s_mov_b32 vcc_hi, 0xaaaaaaaa
	v_mov_b32_dpp v62, v69 quad_perm:[1,0,3,2] row_mask:0xf bank_mask:0xf
	v_mov_b32_dpp v63, v73 quad_perm:[1,0,3,2] row_mask:0xf bank_mask:0xf
	s_nop 1
	v_cndmask_b32_e32 v63, v69, v63, vcc
	v_cndmask_b32_e32 v62, v62, v73, vcc
	v_perm_b32 v62, v62, v63, v64
	global_store_dword v[60:61], v62, off
	v_add_co_u32_e32 v60, vcc, 0x1200, v60
	s_nop 1
	v_addc_co_u32_e32 v61, vcc, 0, v61, vcc
	s_mov_b32 vcc_lo, 0xaaaaaaaa
	s_mov_b32 vcc_hi, 0xaaaaaaaa
	v_mov_b32_dpp v62, v70 quad_perm:[1,0,3,2] row_mask:0xf bank_mask:0xf
	v_mov_b32_dpp v63, v74 quad_perm:[1,0,3,2] row_mask:0xf bank_mask:0xf
	s_nop 1
	v_cndmask_b32_e32 v63, v70, v63, vcc
	v_cndmask_b32_e32 v62, v62, v74, vcc
	v_perm_b32 v62, v62, v63, v64
	global_store_dword v[60:61], v62, off
	v_add_co_u32_e32 v60, vcc, 0x1200, v60
	s_nop 1
	v_addc_co_u32_e32 v61, vcc, 0, v61, vcc
	s_mov_b32 vcc_lo, 0xaaaaaaaa
	s_mov_b32 vcc_hi, 0xaaaaaaaa
	v_mov_b32_dpp v62, v71 quad_perm:[1,0,3,2] row_mask:0xf bank_mask:0xf
	v_mov_b32_dpp v63, v75 quad_perm:[1,0,3,2] row_mask:0xf bank_mask:0xf
	s_nop 1
	v_cndmask_b32_e32 v63, v71, v63, vcc
	v_cndmask_b32_e32 v62, v62, v75, vcc
	v_perm_b32 v62, v62, v63, v64
	global_store_dword v[60:61], v62, off

; __device__ __forceinline__ bfu f2bf(float f) {
;   unsigned u = __float_as_uint(f);
;   u += 0x7fffu + ((u >> 16) & 1u);
;   return (bfu)(u >> 16);
; }
;   __device__ __forceinline__ void operator()(const f32x4 (&acc)[2][2][4][2], const Unit& u, int wr, int wc, int fr, int fq) const {
;     ...
;           } else if (sec == 11) {
;             const int t = tbase + rl;
;             bfu* dst = vt + ((size_t)bb * 512 + (c0 - 5632)) * TPB + t;
; #pragma unroll
;             for (int j = 0; j < 4; ++j) {
;               dst[(size_t)j * TPB] = f2bf(v0[j]);
;               dst[(size_t)(16 + j) * TPB] = f2bf(v1[j]);
;             }
.LBB0_612:
	s_andn2_b64 vcc, exec, s[0:1]
	s_cbranch_vccnz .LBB0_614
	v_readlane_b32 s0, v252, 45
	v_readlane_b32 s1, v252, 46
	s_ashr_i32 s21, s20, 31
	v_lshl_add_u64 v[54:55], s[20:21], 0, v[156:157]
	v_lshl_add_u64 v[52:53], s[0:1], 0, v[90:91]
	v_lshl_add_u64 v[52:53], v[54:55], 1, v[52:53]
	v_bfe_u32 v54, v60, 16, 1
	v_add3_u32 v60, v60, v54, s94
	v_bfe_u32 v54, v61, 16, 1
	v_add3_u32 v61, v61, v54, s94
	v_bfe_u32 v54, v62, 16, 1
	v_add3_u32 v62, v62, v54, s94
	v_bfe_u32 v54, v63, 16, 1
	v_add3_u32 v63, v63, v54, s94
	v_bfe_u32 v54, v64, 16, 1
	v_add3_u32 v64, v64, v54, s94
	v_bfe_u32 v54, v65, 16, 1
	v_add3_u32 v65, v65, v54, s94
	v_bfe_u32 v54, v66, 16, 1
	v_add3_u32 v66, v66, v54, s94
	v_bfe_u32 v54, v67, 16, 1
	v_add3_u32 v67, v67, v54, s94
	s_mov_b32 vcc_lo, 0xaaaaaaaa
	s_mov_b32 vcc_hi, 0xaaaaaaaa
	v_mov_b32_e32 v54, 0x11ffe
	v_mov_b32_e32 v56, 0x7060302
	v_cndmask_b32_e32 v54, 0, v54, vcc
	v_add_co_u32_e32 v52, vcc, v52, v54
	s_nop 1
	v_addc_co_u32_e32 v53, vcc, 0, v53, vcc
	s_mov_b32 vcc_lo, 0xaaaaaaaa
	s_mov_b32 vcc_hi, 0xaaaaaaaa
	v_mov_b32_dpp v54, v60 quad_perm:[1,0,3,2] row_mask:0xf bank_mask:0xf
	v_mov_b32_dpp v55, v64 quad_perm:[1,0,3,2] row_mask:0xf bank_mask:0xf
	s_nop 1
	v_cndmask_b32_e32 v55, v60, v55, vcc
	v_cndmask_b32_e32 v54, v54, v64, vcc
	v_perm_b32 v54, v54, v55, v56
	global_store_dword v[52:53], v54, off offset:32
	v_add_co_u32_e32 v52, vcc, 0x1200, v52
	s_nop 1
	v_addc_co_u32_e32 v53, vcc, 0, v53, vcc
	s_mov_b32 vcc_lo, 0xaaaaaaaa
	s_mov_b32 vcc_hi, 0xaaaaaaaa
	v_mov_b32_dpp v54, v61 quad_perm:[1,0,3,2] row_mask:0xf bank_mask:0xf
	v_mov_b32_dpp v55, v65 quad_perm:[1,0,3,2] row_mask:0xf bank_mask:0xf
	s_nop 1
	v_cndmask_b32_e32 v55, v61, v55, vcc
	v_cndmask_b32_e32 v54, v54, v65, vcc
	v_perm_b32 v54, v54, v55, v56
	global_store_dword v[52:53], v54, off offset:32
	v_add_co_u32_e32 v52, vcc, 0x1200, v52
	s_nop 1
	v_addc_co_u32_e32 v53, vcc, 0, v53, vcc
	s_mov_b32 vcc_lo, 0xaaaaaaaa
	s_mov_b32 vcc_hi, 0xaaaaaaaa
	v_mov_b32_dpp v54, v62 quad_perm:[1,0,3,2] row_mask:0xf bank_mask:0xf
	v_mov_b32_dpp v55, v66 quad_perm:[1,0,3,2] row_mask:0xf bank_mask:0xf
	s_nop 1
	v_cndmask_b32_e32 v55, v62, v55, vcc
	v_cndmask_b32_e32 v54, v54, v66, vcc
	v_perm_b32 v54, v54, v55, v56
	global_store_dword v[52:53], v54, off offset:32
	v_add_co_u32_e32 v52, vcc, 0x1200, v52
	s_nop 1
	v_addc_co_u32_e32 v53, vcc, 0, v53, vcc
	s_mov_b32 vcc_lo, 0xaaaaaaaa
	s_mov_b32 vcc_hi, 0xaaaaaaaa
	v_mov_b32_dpp v54, v63 quad_perm:[1,0,3,2] row_mask:0xf bank_mask:0xf
	v_mov_b32_dpp v55, v67 quad_perm:[1,0,3,2] row_mask:0xf bank_mask:0xf
	s_nop 1
	v_cndmask_b32_e32 v55, v63, v55, vcc
	v_cndmask_b32_e32 v54, v54, v67, vcc
	v_perm_b32 v54, v54, v55, v56
	global_store_dword v[52:53], v54, off offset:32

; __device__ __forceinline__ bfu f2bf(float f) {
;   unsigned u = __float_as_uint(f);
;   u += 0x7fffu + ((u >> 16) & 1u);
;   return (bfu)(u >> 16);
; }
;   __device__ __forceinline__ void operator()(const f32x4 (&acc)[2][2][4][2], const Unit& u, int wr, int wc, int fr, int fq) const {
;     ...
;           } else if (sec == 11) {
;             const int t = tbase + rl;
;             bfu* dst = vt + ((size_t)bb * 512 + (c0 - 5632)) * TPB + t;
; #pragma unroll
;             for (int j = 0; j < 4; ++j) {
;               dst[(size_t)j * TPB] = f2bf(v0[j]);
;               dst[(size_t)(16 + j) * TPB] = f2bf(v1[j]);
;             }
.LBB0_638:
	s_andn2_b64 vcc, exec, s[0:1]
	s_cbranch_vccnz .LBB0_640
	v_readlane_b32 s0, v252, 45
	v_readlane_b32 s1, v252, 46
	s_ashr_i32 s21, s20, 31
	v_lshl_add_u64 v[46:47], s[20:21], 0, v[156:157]
	v_lshl_add_u64 v[44:45], s[0:1], 0, v[90:91]
	v_lshl_add_u64 v[44:45], v[46:47], 1, v[44:45]
	v_bfe_u32 v46, v52, 16, 1
	v_add3_u32 v52, v52, v46, s94
	v_bfe_u32 v46, v53, 16, 1
	v_add3_u32 v53, v53, v46, s94
	v_bfe_u32 v46, v54, 16, 1
	v_add3_u32 v54, v54, v46, s94
	v_bfe_u32 v46, v55, 16, 1
	v_add3_u32 v55, v55, v46, s94
	v_bfe_u32 v46, v56, 16, 1
	v_add3_u32 v56, v56, v46, s94
	v_bfe_u32 v46, v57, 16, 1
	v_add3_u32 v57, v57, v46, s94
	v_bfe_u32 v46, v58, 16, 1
	v_add3_u32 v58, v58, v46, s94
	v_bfe_u32 v46, v59, 16, 1
	v_add3_u32 v59, v59, v46, s94
	s_mov_b32 vcc_lo, 0xaaaaaaaa
	s_mov_b32 vcc_hi, 0xaaaaaaaa
	v_mov_b32_e32 v46, 0x11ffe
	v_mov_b32_e32 v48, 0x7060302
	v_cndmask_b32_e32 v46, 0, v46, vcc
	v_add_co_u32_e32 v44, vcc, v44, v46
	s_nop 1
	v_addc_co_u32_e32 v45, vcc, 0, v45, vcc
	s_mov_b32 vcc_lo, 0xaaaaaaaa
	s_mov_b32 vcc_hi, 0xaaaaaaaa
	v_mov_b32_dpp v46, v52 quad_perm:[1,0,3,2] row_mask:0xf bank_mask:0xf
	v_mov_b32_dpp v47, v56 quad_perm:[1,0,3,2] row_mask:0xf bank_mask:0xf
	s_nop 1
	v_cndmask_b32_e32 v47, v52, v47, vcc
	v_cndmask_b32_e32 v46, v46, v56, vcc
	v_perm_b32 v46, v46, v47, v48
	global_store_dword v[44:45], v46, off offset:64
	v_add_co_u32_e32 v44, vcc, 0x1200, v44
	s_nop 1
	v_addc_co_u32_e32 v45, vcc, 0, v45, vcc
	s_mov_b32 vcc_lo, 0xaaaaaaaa
	s_mov_b32 vcc_hi, 0xaaaaaaaa
	v_mov_b32_dpp v46, v53 quad_perm:[1,0,3,2] row_mask:0xf bank_mask:0xf
	v_mov_b32_dpp v47, v57 quad_perm:[1,0,3,2] row_mask:0xf bank_mask:0xf
	s_nop 1
	v_cndmask_b32_e32 v47, v53, v47, vcc
	v_cndmask_b32_e32 v46, v46, v57, vcc
	v_perm_b32 v46, v46, v47, v48
	global_store_dword v[44:45], v46, off offset:64
	v_add_co_u32_e32 v44, vcc, 0x1200, v44
	s_nop 1
	v_addc_co_u32_e32 v45, vcc, 0, v45, vcc
	s_mov_b32 vcc_lo, 0xaaaaaaaa
	s_mov_b32 vcc_hi, 0xaaaaaaaa
	v_mov_b32_dpp v46, v54 quad_perm:[1,0,3,2] row_mask:0xf bank_mask:0xf
	v_mov_b32_dpp v47, v58 quad_perm:[1,0,3,2] row_mask:0xf bank_mask:0xf
	s_nop 1
	v_cndmask_b32_e32 v47, v54, v47, vcc
	v_cndmask_b32_e32 v46, v46, v58, vcc
	v_perm_b32 v46, v46, v47, v48
	global_store_dword v[44:45], v46, off offset:64
	v_add_co_u32_e32 v44, vcc, 0x1200, v44
	s_nop 1
	v_addc_co_u32_e32 v45, vcc, 0, v45, vcc
	s_mov_b32 vcc_lo, 0xaaaaaaaa
	s_mov_b32 vcc_hi, 0xaaaaaaaa
	v_mov_b32_dpp v46, v55 quad_perm:[1,0,3,2] row_mask:0xf bank_mask:0xf
	v_mov_b32_dpp v47, v59 quad_perm:[1,0,3,2] row_mask:0xf bank_mask:0xf
	s_nop 1
	v_cndmask_b32_e32 v47, v55, v47, vcc
	v_cndmask_b32_e32 v46, v46, v59, vcc
	v_perm_b32 v46, v46, v47, v48
	global_store_dword v[44:45], v46, off offset:64

; __device__ __forceinline__ bfu f2bf(float f) {
;   unsigned u = __float_as_uint(f);
;   u += 0x7fffu + ((u >> 16) & 1u);
;   return (bfu)(u >> 16);
; }
;   __device__ __forceinline__ void operator()(const f32x4 (&acc)[2][2][4][2], const Unit& u, int wr, int wc, int fr, int fq) const {
;     ...
;           } else if (sec == 11) {
;             const int t = tbase + rl;
;             bfu* dst = vt + ((size_t)bb * 512 + (c0 - 5632)) * TPB + t;
; #pragma unroll
;             for (int j = 0; j < 4; ++j) {
;               dst[(size_t)j * TPB] = f2bf(v0[j]);
;               dst[(size_t)(16 + j) * TPB] = f2bf(v1[j]);
;             }
.LBB0_664:
	s_andn2_b64 vcc, exec, s[0:1]
	s_cbranch_vccnz .LBB0_666
	v_readlane_b32 s0, v252, 45
	v_readlane_b32 s1, v252, 46
	s_ashr_i32 s21, s20, 31
	v_lshl_add_u64 v[38:39], s[20:21], 0, v[156:157]
	v_lshl_add_u64 v[36:37], s[0:1], 0, v[90:91]
	v_lshl_add_u64 v[36:37], v[38:39], 1, v[36:37]
	v_bfe_u32 v38, v44, 16, 1
	v_add3_u32 v44, v44, v38, s94
	v_bfe_u32 v38, v45, 16, 1
	v_add3_u32 v45, v45, v38, s94
	v_bfe_u32 v38, v46, 16, 1
	v_add3_u32 v46, v46, v38, s94
	v_bfe_u32 v38, v47, 16, 1
	v_add3_u32 v47, v47, v38, s94
	v_bfe_u32 v38, v48, 16, 1
	v_add3_u32 v48, v48, v38, s94
	v_bfe_u32 v38, v49, 16, 1
	v_add3_u32 v49, v49, v38, s94
	v_bfe_u32 v38, v50, 16, 1
	v_add3_u32 v50, v50, v38, s94
	v_bfe_u32 v38, v51, 16, 1
	v_add3_u32 v51, v51, v38, s94
	s_mov_b32 vcc_lo, 0xaaaaaaaa
	s_mov_b32 vcc_hi, 0xaaaaaaaa
	v_mov_b32_e32 v38, 0x11ffe
	v_mov_b32_e32 v40, 0x7060302
	v_cndmask_b32_e32 v38, 0, v38, vcc
	v_add_co_u32_e32 v36, vcc, v36, v38
	s_nop 1
	v_addc_co_u32_e32 v37, vcc, 0, v37, vcc
	s_mov_b32 vcc_lo, 0xaaaaaaaa
	s_mov_b32 vcc_hi, 0xaaaaaaaa
	v_mov_b32_dpp v38, v44 quad_perm:[1,0,3,2] row_mask:0xf bank_mask:0xf
	v_mov_b32_dpp v39, v48 quad_perm:[1,0,3,2] row_mask:0xf bank_mask:0xf
	s_nop 1
	v_cndmask_b32_e32 v39, v44, v39, vcc
	v_cndmask_b32_e32 v38, v38, v48, vcc
	v_perm_b32 v38, v38, v39, v40
	global_store_dword v[36:37], v38, off offset:96
	v_add_co_u32_e32 v36, vcc, 0x1200, v36
	s_nop 1
	v_addc_co_u32_e32 v37, vcc, 0, v37, vcc
	s_mov_b32 vcc_lo, 0xaaaaaaaa
	s_mov_b32 vcc_hi, 0xaaaaaaaa
	v_mov_b32_dpp v38, v45 quad_perm:[1,0,3,2] row_mask:0xf bank_mask:0xf
	v_mov_b32_dpp v39, v49 quad_perm:[1,0,3,2] row_mask:0xf bank_mask:0xf
	s_nop 1
	v_cndmask_b32_e32 v39, v45, v39, vcc
	v_cndmask_b32_e32 v38, v38, v49, vcc
	v_perm_b32 v38, v38, v39, v40
	global_store_dword v[36:37], v38, off offset:96
	v_add_co_u32_e32 v36, vcc, 0x1200, v36
	s_nop 1
	v_addc_co_u32_e32 v37, vcc, 0, v37, vcc
	s_mov_b32 vcc_lo, 0xaaaaaaaa
	s_mov_b32 vcc_hi, 0xaaaaaaaa
	v_mov_b32_dpp v38, v46 quad_perm:[1,0,3,2] row_mask:0xf bank_mask:0xf
	v_mov_b32_dpp v39, v50 quad_perm:[1,0,3,2] row_mask:0xf bank_mask:0xf
	s_nop 1
	v_cndmask_b32_e32 v39, v46, v39, vcc
	v_cndmask_b32_e32 v38, v38, v50, vcc
	v_perm_b32 v38, v38, v39, v40
	global_store_dword v[36:37], v38, off offset:96
	v_add_co_u32_e32 v36, vcc, 0x1200, v36
	s_nop 1
	v_addc_co_u32_e32 v37, vcc, 0, v37, vcc
	s_mov_b32 vcc_lo, 0xaaaaaaaa
	s_mov_b32 vcc_hi, 0xaaaaaaaa
	v_mov_b32_dpp v38, v47 quad_perm:[1,0,3,2] row_mask:0xf bank_mask:0xf
	v_mov_b32_dpp v39, v51 quad_perm:[1,0,3,2] row_mask:0xf bank_mask:0xf
	s_nop 1
	v_cndmask_b32_e32 v39, v47, v39, vcc
	v_cndmask_b32_e32 v38, v38, v51, vcc
	v_perm_b32 v38, v38, v39, v40
	global_store_dword v[36:37], v38, off offset:96

; __device__ __forceinline__ bfu f2bf(float f) {
;   unsigned u = __float_as_uint(f);
;   u += 0x7fffu + ((u >> 16) & 1u);
;   return (bfu)(u >> 16);
; }
;   __device__ __forceinline__ void operator()(const f32x4 (&acc)[2][2][4][2], const Unit& u, int wr, int wc, int fr, int fq) const {
;     ...
;           } else if (sec == 11) {
;             const int t = tbase + rl;
;             bfu* dst = vt + ((size_t)bb * 512 + (c0 - 5632)) * TPB + t;
; #pragma unroll
;             for (int j = 0; j < 4; ++j) {
;               dst[(size_t)j * TPB] = f2bf(v0[j]);
;               dst[(size_t)(16 + j) * TPB] = f2bf(v1[j]);
;             }
.LBB0_690:
	s_andn2_b64 vcc, exec, s[0:1]
	s_cbranch_vccnz .LBB0_692
	v_readlane_b32 s0, v252, 45
	v_readlane_b32 s1, v252, 46
	s_ashr_i32 s21, s20, 31
	v_lshl_add_u64 v[30:31], s[20:21], 0, v[156:157]
	v_lshl_add_u64 v[28:29], s[0:1], 0, v[90:91]
	v_lshl_add_u64 v[28:29], v[30:31], 1, v[28:29]
	v_bfe_u32 v30, v36, 16, 1
	v_add3_u32 v36, v36, v30, s94
	v_bfe_u32 v30, v37, 16, 1
	v_add3_u32 v37, v37, v30, s94
	v_bfe_u32 v30, v38, 16, 1
	v_add3_u32 v38, v38, v30, s94
	v_bfe_u32 v30, v39, 16, 1
	v_add3_u32 v39, v39, v30, s94
	v_bfe_u32 v30, v40, 16, 1
	v_add3_u32 v40, v40, v30, s94
	v_bfe_u32 v30, v41, 16, 1
	v_add3_u32 v41, v41, v30, s94
	v_bfe_u32 v30, v42, 16, 1
	v_add3_u32 v42, v42, v30, s94
	v_bfe_u32 v30, v43, 16, 1
	v_add3_u32 v43, v43, v30, s94
	s_mov_b32 vcc_lo, 0xaaaaaaaa
	s_mov_b32 vcc_hi, 0xaaaaaaaa
	v_mov_b32_e32 v30, 0x11ffe
	v_mov_b32_e32 v32, 0x7060302
	v_cndmask_b32_e32 v30, 0, v30, vcc
	v_add_co_u32_e32 v28, vcc, v28, v30
	s_nop 1
	v_addc_co_u32_e32 v29, vcc, 0, v29, vcc
	s_mov_b32 vcc_lo, 0xaaaaaaaa
	s_mov_b32 vcc_hi, 0xaaaaaaaa
	v_mov_b32_dpp v30, v36 quad_perm:[1,0,3,2] row_mask:0xf bank_mask:0xf
	v_mov_b32_dpp v31, v40 quad_perm:[1,0,3,2] row_mask:0xf bank_mask:0xf
	s_nop 1
	v_cndmask_b32_e32 v31, v36, v31, vcc
	v_cndmask_b32_e32 v30, v30, v40, vcc
	v_perm_b32 v30, v30, v31, v32
	global_store_dword v[28:29], v30, off offset:256
	v_add_co_u32_e32 v28, vcc, 0x1200, v28
	s_nop 1
	v_addc_co_u32_e32 v29, vcc, 0, v29, vcc
	s_mov_b32 vcc_lo, 0xaaaaaaaa
	s_mov_b32 vcc_hi, 0xaaaaaaaa
	v_mov_b32_dpp v30, v37 quad_perm:[1,0,3,2] row_mask:0xf bank_mask:0xf
	v_mov_b32_dpp v31, v41 quad_perm:[1,0,3,2] row_mask:0xf bank_mask:0xf
	s_nop 1
	v_cndmask_b32_e32 v31, v37, v31, vcc
	v_cndmask_b32_e32 v30, v30, v41, vcc
	v_perm_b32 v30, v30, v31, v32
	global_store_dword v[28:29], v30, off offset:256
	v_add_co_u32_e32 v28, vcc, 0x1200, v28
	s_nop 1
	v_addc_co_u32_e32 v29, vcc, 0, v29, vcc
	s_mov_b32 vcc_lo, 0xaaaaaaaa
	s_mov_b32 vcc_hi, 0xaaaaaaaa
	v_mov_b32_dpp v30, v38 quad_perm:[1,0,3,2] row_mask:0xf bank_mask:0xf
	v_mov_b32_dpp v31, v42 quad_perm:[1,0,3,2] row_mask:0xf bank_mask:0xf
	s_nop 1
	v_cndmask_b32_e32 v31, v38, v31, vcc
	v_cndmask_b32_e32 v30, v30, v42, vcc
	v_perm_b32 v30, v30, v31, v32
	global_store_dword v[28:29], v30, off offset:256
	v_add_co_u32_e32 v28, vcc, 0x1200, v28
	s_nop 1
	v_addc_co_u32_e32 v29, vcc, 0, v29, vcc
	s_mov_b32 vcc_lo, 0xaaaaaaaa
	s_mov_b32 vcc_hi, 0xaaaaaaaa
	v_mov_b32_dpp v30, v39 quad_perm:[1,0,3,2] row_mask:0xf bank_mask:0xf
	v_mov_b32_dpp v31, v43 quad_perm:[1,0,3,2] row_mask:0xf bank_mask:0xf
	s_nop 1
	v_cndmask_b32_e32 v31, v39, v31, vcc
	v_cndmask_b32_e32 v30, v30, v43, vcc
	v_perm_b32 v30, v30, v31, v32
	global_store_dword v[28:29], v30, off offset:256

; __device__ __forceinline__ bfu f2bf(float f) {
;   unsigned u = __float_as_uint(f);
;   u += 0x7fffu + ((u >> 16) & 1u);
;   return (bfu)(u >> 16);
; }
;   __device__ __forceinline__ void operator()(const f32x4 (&acc)[2][2][4][2], const Unit& u, int wr, int wc, int fr, int fq) const {
;     ...
;           } else if (sec == 11) {
;             const int t = tbase + rl;
;             bfu* dst = vt + ((size_t)bb * 512 + (c0 - 5632)) * TPB + t;
; #pragma unroll
;             for (int j = 0; j < 4; ++j) {
;               dst[(size_t)j * TPB] = f2bf(v0[j]);
;               dst[(size_t)(16 + j) * TPB] = f2bf(v1[j]);
;             }
.LBB0_716:
	s_andn2_b64 vcc, exec, s[0:1]
	s_cbranch_vccnz .LBB0_718
	v_readlane_b32 s0, v252, 45
	v_readlane_b32 s1, v252, 46
	s_ashr_i32 s21, s20, 31
	v_lshl_add_u64 v[22:23], s[20:21], 0, v[156:157]
	v_lshl_add_u64 v[20:21], s[0:1], 0, v[90:91]
	v_lshl_add_u64 v[20:21], v[22:23], 1, v[20:21]
	v_bfe_u32 v22, v28, 16, 1
	v_add3_u32 v28, v28, v22, s94
	v_bfe_u32 v22, v29, 16, 1
	v_add3_u32 v29, v29, v22, s94
	v_bfe_u32 v22, v30, 16, 1
	v_add3_u32 v30, v30, v22, s94
	v_bfe_u32 v22, v31, 16, 1
	v_add3_u32 v31, v31, v22, s94
	v_bfe_u32 v22, v32, 16, 1
	v_add3_u32 v32, v32, v22, s94
	v_bfe_u32 v22, v33, 16, 1
	v_add3_u32 v33, v33, v22, s94
	v_bfe_u32 v22, v34, 16, 1
	v_add3_u32 v34, v34, v22, s94
	v_bfe_u32 v22, v35, 16, 1
	v_add3_u32 v35, v35, v22, s94
	s_mov_b32 vcc_lo, 0xaaaaaaaa
	s_mov_b32 vcc_hi, 0xaaaaaaaa
	v_mov_b32_e32 v22, 0x11ffe
	v_mov_b32_e32 v24, 0x7060302
	v_cndmask_b32_e32 v22, 0, v22, vcc
	v_add_co_u32_e32 v20, vcc, v20, v22
	s_nop 1
	v_addc_co_u32_e32 v21, vcc, 0, v21, vcc
	s_mov_b32 vcc_lo, 0xaaaaaaaa
	s_mov_b32 vcc_hi, 0xaaaaaaaa
	v_mov_b32_dpp v22, v28 quad_perm:[1,0,3,2] row_mask:0xf bank_mask:0xf
	v_mov_b32_dpp v23, v32 quad_perm:[1,0,3,2] row_mask:0xf bank_mask:0xf
	s_nop 1
	v_cndmask_b32_e32 v23, v28, v23, vcc
	v_cndmask_b32_e32 v22, v22, v32, vcc
	v_perm_b32 v22, v22, v23, v24
	global_store_dword v[20:21], v22, off offset:288
	v_add_co_u32_e32 v20, vcc, 0x1200, v20
	s_nop 1
	v_addc_co_u32_e32 v21, vcc, 0, v21, vcc
	s_mov_b32 vcc_lo, 0xaaaaaaaa
	s_mov_b32 vcc_hi, 0xaaaaaaaa
	v_mov_b32_dpp v22, v29 quad_perm:[1,0,3,2] row_mask:0xf bank_mask:0xf
	v_mov_b32_dpp v23, v33 quad_perm:[1,0,3,2] row_mask:0xf bank_mask:0xf
	s_nop 1
	v_cndmask_b32_e32 v23, v29, v23, vcc
	v_cndmask_b32_e32 v22, v22, v33, vcc
	v_perm_b32 v22, v22, v23, v24
	global_store_dword v[20:21], v22, off offset:288
	v_add_co_u32_e32 v20, vcc, 0x1200, v20
	s_nop 1
	v_addc_co_u32_e32 v21, vcc, 0, v21, vcc
	s_mov_b32 vcc_lo, 0xaaaaaaaa
	s_mov_b32 vcc_hi, 0xaaaaaaaa
	v_mov_b32_dpp v22, v30 quad_perm:[1,0,3,2] row_mask:0xf bank_mask:0xf
	v_mov_b32_dpp v23, v34 quad_perm:[1,0,3,2] row_mask:0xf bank_mask:0xf
	s_nop 1
	v_cndmask_b32_e32 v23, v30, v23, vcc
	v_cndmask_b32_e32 v22, v22, v34, vcc
	v_perm_b32 v22, v22, v23, v24
	global_store_dword v[20:21], v22, off offset:288
	v_add_co_u32_e32 v20, vcc, 0x1200, v20
	s_nop 1
	v_addc_co_u32_e32 v21, vcc, 0, v21, vcc
	s_mov_b32 vcc_lo, 0xaaaaaaaa
	s_mov_b32 vcc_hi, 0xaaaaaaaa
	v_mov_b32_dpp v22, v31 quad_perm:[1,0,3,2] row_mask:0xf bank_mask:0xf
	v_mov_b32_dpp v23, v35 quad_perm:[1,0,3,2] row_mask:0xf bank_mask:0xf
	s_nop 1
	v_cndmask_b32_e32 v23, v31, v23, vcc
	v_cndmask_b32_e32 v22, v22, v35, vcc
	v_perm_b32 v22, v22, v23, v24
	global_store_dword v[20:21], v22, off offset:288

; __device__ __forceinline__ bfu f2bf(float f) {
;   unsigned u = __float_as_uint(f);
;   u += 0x7fffu + ((u >> 16) & 1u);
;   return (bfu)(u >> 16);
; }
;   __device__ __forceinline__ void operator()(const f32x4 (&acc)[2][2][4][2], const Unit& u, int wr, int wc, int fr, int fq) const {
;     ...
;           } else if (sec == 11) {
;             const int t = tbase + rl;
;             bfu* dst = vt + ((size_t)bb * 512 + (c0 - 5632)) * TPB + t;
; #pragma unroll
;             for (int j = 0; j < 4; ++j) {
;               dst[(size_t)j * TPB] = f2bf(v0[j]);
;               dst[(size_t)(16 + j) * TPB] = f2bf(v1[j]);
;             }
.LBB0_742:
	s_andn2_b64 vcc, exec, s[0:1]
	s_cbranch_vccnz .LBB0_744
	v_readlane_b32 s0, v252, 45
	v_readlane_b32 s1, v252, 46
	s_ashr_i32 s21, s20, 31
	v_lshl_add_u64 v[10:11], s[20:21], 0, v[156:157]
	v_lshl_add_u64 v[8:9], s[0:1], 0, v[90:91]
	v_lshl_add_u64 v[8:9], v[10:11], 1, v[8:9]
	v_bfe_u32 v10, v20, 16, 1
	v_add3_u32 v20, v20, v10, s94
	v_bfe_u32 v10, v21, 16, 1
	v_add3_u32 v21, v21, v10, s94
	v_bfe_u32 v10, v22, 16, 1
	v_add3_u32 v22, v22, v10, s94
	v_bfe_u32 v10, v23, 16, 1
	v_add3_u32 v23, v23, v10, s94
	v_bfe_u32 v10, v24, 16, 1
	v_add3_u32 v24, v24, v10, s94
	v_bfe_u32 v10, v25, 16, 1
	v_add3_u32 v25, v25, v10, s94
	v_bfe_u32 v10, v26, 16, 1
	v_add3_u32 v26, v26, v10, s94
	v_bfe_u32 v10, v27, 16, 1
	v_add3_u32 v27, v27, v10, s94
	s_mov_b32 vcc_lo, 0xaaaaaaaa
	s_mov_b32 vcc_hi, 0xaaaaaaaa
	v_mov_b32_e32 v10, 0x11ffe
	v_mov_b32_e32 v12, 0x7060302
	v_cndmask_b32_e32 v10, 0, v10, vcc
	v_add_co_u32_e32 v8, vcc, v8, v10
	s_nop 1
	v_addc_co_u32_e32 v9, vcc, 0, v9, vcc
	s_mov_b32 vcc_lo, 0xaaaaaaaa
	s_mov_b32 vcc_hi, 0xaaaaaaaa
	v_mov_b32_dpp v10, v20 quad_perm:[1,0,3,2] row_mask:0xf bank_mask:0xf
	v_mov_b32_dpp v11, v24 quad_perm:[1,0,3,2] row_mask:0xf bank_mask:0xf
	s_nop 1
	v_cndmask_b32_e32 v11, v20, v11, vcc
	v_cndmask_b32_e32 v10, v10, v24, vcc
	v_perm_b32 v10, v10, v11, v12
	global_store_dword v[8:9], v10, off offset:320
	v_add_co_u32_e32 v8, vcc, 0x1200, v8
	s_nop 1
	v_addc_co_u32_e32 v9, vcc, 0, v9, vcc
	s_mov_b32 vcc_lo, 0xaaaaaaaa
	s_mov_b32 vcc_hi, 0xaaaaaaaa
	v_mov_b32_dpp v10, v21 quad_perm:[1,0,3,2] row_mask:0xf bank_mask:0xf
	v_mov_b32_dpp v11, v25 quad_perm:[1,0,3,2] row_mask:0xf bank_mask:0xf
	s_nop 1
	v_cndmask_b32_e32 v11, v21, v11, vcc
	v_cndmask_b32_e32 v10, v10, v25, vcc
	v_perm_b32 v10, v10, v11, v12
	global_store_dword v[8:9], v10, off offset:320
	v_add_co_u32_e32 v8, vcc, 0x1200, v8
	s_nop 1
	v_addc_co_u32_e32 v9, vcc, 0, v9, vcc
	s_mov_b32 vcc_lo, 0xaaaaaaaa
	s_mov_b32 vcc_hi, 0xaaaaaaaa
	v_mov_b32_dpp v10, v22 quad_perm:[1,0,3,2] row_mask:0xf bank_mask:0xf
	v_mov_b32_dpp v11, v26 quad_perm:[1,0,3,2] row_mask:0xf bank_mask:0xf
	s_nop 1
	v_cndmask_b32_e32 v11, v22, v11, vcc
	v_cndmask_b32_e32 v10, v10, v26, vcc
	v_perm_b32 v10, v10, v11, v12
	global_store_dword v[8:9], v10, off offset:320
	v_add_co_u32_e32 v8, vcc, 0x1200, v8
	s_nop 1
	v_addc_co_u32_e32 v9, vcc, 0, v9, vcc
	s_mov_b32 vcc_lo, 0xaaaaaaaa
	s_mov_b32 vcc_hi, 0xaaaaaaaa
	v_mov_b32_dpp v10, v23 quad_perm:[1,0,3,2] row_mask:0xf bank_mask:0xf
	v_mov_b32_dpp v11, v27 quad_perm:[1,0,3,2] row_mask:0xf bank_mask:0xf
	s_nop 1
	v_cndmask_b32_e32 v11, v23, v11, vcc
	v_cndmask_b32_e32 v10, v10, v27, vcc
	v_perm_b32 v10, v10, v11, v12
	global_store_dword v[8:9], v10, off offset:320

; __device__ __forceinline__ bfu f2bf(float f) {
;   unsigned u = __float_as_uint(f);
;   u += 0x7fffu + ((u >> 16) & 1u);
;   return (bfu)(u >> 16);
; }
;   __device__ __forceinline__ void operator()(const f32x4 (&acc)[2][2][4][2], const Unit& u, int wr, int wc, int fr, int fq) const {
;     ...
;           } else if (sec == 11) {
;             const int t = tbase + rl;
;             bfu* dst = vt + ((size_t)bb * 512 + (c0 - 5632)) * TPB + t;
; #pragma unroll
;             for (int j = 0; j < 4; ++j) {
;               dst[(size_t)j * TPB] = f2bf(v0[j]);
;               dst[(size_t)(16 + j) * TPB] = f2bf(v1[j]);
;             }
.LBB0_770:
	s_andn2_b64 vcc, exec, s[0:1]
	s_cbranch_vccnz .LBB0_772
	v_readlane_b32 s0, v252, 45
	v_readlane_b32 s1, v252, 46
	s_ashr_i32 s21, s20, 31
	v_lshl_add_u64 v[2:3], s[20:21], 0, v[156:157]
	v_lshl_add_u64 v[0:1], s[0:1], 0, v[90:91]
	v_lshl_add_u64 v[0:1], v[2:3], 1, v[0:1]
	v_bfe_u32 v2, v8, 16, 1
	v_add3_u32 v8, v8, v2, s94
	v_bfe_u32 v2, v9, 16, 1
	v_add3_u32 v9, v9, v2, s94
	v_bfe_u32 v2, v10, 16, 1
	v_add3_u32 v10, v10, v2, s94
	v_bfe_u32 v2, v11, 16, 1
	v_add3_u32 v11, v11, v2, s94
	v_bfe_u32 v2, v12, 16, 1
	v_add3_u32 v12, v12, v2, s94
	v_bfe_u32 v2, v13, 16, 1
	v_add3_u32 v13, v13, v2, s94
	v_bfe_u32 v2, v14, 16, 1
	v_add3_u32 v14, v14, v2, s94
	v_bfe_u32 v2, v15, 16, 1
	v_add3_u32 v15, v15, v2, s94
	s_mov_b32 vcc_lo, 0xaaaaaaaa
	s_mov_b32 vcc_hi, 0xaaaaaaaa
	v_mov_b32_e32 v2, 0x11ffe
	v_mov_b32_e32 v4, 0x7060302
	v_cndmask_b32_e32 v2, 0, v2, vcc
	v_add_co_u32_e32 v0, vcc, v0, v2
	s_nop 1
	v_addc_co_u32_e32 v1, vcc, 0, v1, vcc
	s_mov_b32 vcc_lo, 0xaaaaaaaa
	s_mov_b32 vcc_hi, 0xaaaaaaaa
	v_mov_b32_dpp v2, v8 quad_perm:[1,0,3,2] row_mask:0xf bank_mask:0xf
	v_mov_b32_dpp v3, v12 quad_perm:[1,0,3,2] row_mask:0xf bank_mask:0xf
	s_nop 1
	v_cndmask_b32_e32 v3, v8, v3, vcc
	v_cndmask_b32_e32 v2, v2, v12, vcc
	v_perm_b32 v2, v2, v3, v4
	global_store_dword v[0:1], v2, off offset:352
	v_add_co_u32_e32 v0, vcc, 0x1200, v0
	s_nop 1
	v_addc_co_u32_e32 v1, vcc, 0, v1, vcc
	s_mov_b32 vcc_lo, 0xaaaaaaaa
	s_mov_b32 vcc_hi, 0xaaaaaaaa
	v_mov_b32_dpp v2, v9 quad_perm:[1,0,3,2] row_mask:0xf bank_mask:0xf
	v_mov_b32_dpp v3, v13 quad_perm:[1,0,3,2] row_mask:0xf bank_mask:0xf
	s_nop 1
	v_cndmask_b32_e32 v3, v9, v3, vcc
	v_cndmask_b32_e32 v2, v2, v13, vcc
	v_perm_b32 v2, v2, v3, v4
	global_store_dword v[0:1], v2, off offset:352
	v_add_co_u32_e32 v0, vcc, 0x1200, v0
	s_nop 1
	v_addc_co_u32_e32 v1, vcc, 0, v1, vcc
	s_mov_b32 vcc_lo, 0xaaaaaaaa
	s_mov_b32 vcc_hi, 0xaaaaaaaa
	v_mov_b32_dpp v2, v10 quad_perm:[1,0,3,2] row_mask:0xf bank_mask:0xf
	v_mov_b32_dpp v3, v14 quad_perm:[1,0,3,2] row_mask:0xf bank_mask:0xf
	s_nop 1
	v_cndmask_b32_e32 v3, v10, v3, vcc
	v_cndmask_b32_e32 v2, v2, v14, vcc
	v_perm_b32 v2, v2, v3, v4
	global_store_dword v[0:1], v2, off offset:352
	v_add_co_u32_e32 v0, vcc, 0x1200, v0
	s_nop 1
	v_addc_co_u32_e32 v1, vcc, 0, v1, vcc
	s_mov_b32 vcc_lo, 0xaaaaaaaa
	s_mov_b32 vcc_hi, 0xaaaaaaaa
	v_mov_b32_dpp v2, v11 quad_perm:[1,0,3,2] row_mask:0xf bank_mask:0xf
	v_mov_b32_dpp v3, v15 quad_perm:[1,0,3,2] row_mask:0xf bank_mask:0xf
	s_nop 1
	v_cndmask_b32_e32 v3, v11, v3, vcc
	v_cndmask_b32_e32 v2, v2, v15, vcc
	v_perm_b32 v2, v2, v3, v4
	global_store_dword v[0:1], v2, off offset:352
